# attention: next-tile row max hoisted into PV gaps + n->s copies in PV gaps for both units (skip flag), on top of v17
# speedup vs baseline: 1.0071x; 1.0063x over previous
; #define LAS __attribute__((address_space(3)))
; DI int obid() { int t = blockIdx.x; asm volatile("" : "+s"(t)); return t; }
; DI int ogrid() { int t = gridDim.x; asm volatile("" : "+s"(t)); return t; }
; DI int otid() { int t = threadIdx.x; asm volatile("" : "+v"(t)); return t; }
; DI unsigned char* opq(unsigned char* p) { asm volatile("" : "+s"(p)); return p; }
; #define P (kparams())
; DI void attn_unit(LAS unsigned char* lds, const bf16_t* __restrict__ Q, const bf16_t* __restrict__ Kg, const bf16_t* __restrict__ VT, bf16_t* __restrict__ MIX, int b, int h, int c0, int nq, int desc) {
;   const int tid = otid(), wave = tid >> 6, lane = tid & 63, r31 = lane & 31, hh = lane >> 5;
;   const bool active = (wave >> 1) < nq; const int cq = c0 + (wave >> 1); const int nt = c0 + nq;
;   const size_t qrow = (size_t)b * LP + 64 * c0 + (active ? 32 * wave + r31 : 0);
;   bf16x8 qf[12];
;   { const bf16_t* qp = Q + qrow * 768 + h * 192 + 8 * hh;
; #pragma unroll
;     for (int s = 0; s < 12; ++s) qf[s] = *(const bf16x8*)(qp + 16 * s); }
;   f32x16 O[4];
; #pragma unroll
;   for (int d = 0; d < 4; ++d)
; #pragma unroll
;     for (int i = 0; i < 16; ++i) O[d][i] = 0.f;
;   float mrun = NEG_INF, lrun = 0.f;
;   const bf16_t* kbase = Kg + (size_t)b * LP * 768 + h * 192;
;   const bf16_t* vbase = VT + (size_t)(b * 4 + h) * 128 * LP;
; DI void phase_attn(KP P, LAS unsigned char* lds) {
;   const bf16_t* Q = (const bf16_t*)(opq(P->ws) + OFF_BIG + B_QP); const bf16_t* Kg = (const bf16_t*)(opq(P->ws) + OFF_BIG + B_KK); const bf16_t* VT = (const bf16_t*)(opq(P->ws) + OFF_BIG + B_VT);
;   bf16_t* MIX = (bf16_t*)(opq(P->ws) + OFF_U);
;   for (int j = obid(); j < 256; j += ogrid()) {
;     const int bh = j & 7, pi = j >> 3; const int b = bh >> 2, h = bh & 3;
;     attn_unit(lds, Q, Kg, VT, MIX, b, h, 4 * (64 - pi) - 3, 4, 0);
.LBB0_526:
	s_or_b64 exec, exec, s[58:59]
	s_mov_b64 s[4:5], s[88:89]
	s_waitcnt lgkmcnt(0)
	s_barrier
	s_load_dwordx2 s[4:5], s[4:5], 0x98
	s_mov_b32 s3, s2
	s_waitcnt lgkmcnt(0)
	s_mov_b64 s[8:9], s[4:5]
	s_mov_b64 s[6:7], s[4:5]
	s_mov_b64 s[10:11], s[4:5]
	s_cmpk_gt_i32 s3, 0xff
	s_cbranch_scc1 .LBB0_627
	s_add_u32 s8, s8, 0x12712000
	s_addc_u32 s9, s9, 0
	s_add_u32 s33, s6, 0x15772000
	s_addc_u32 s36, s7, 0
	s_add_u32 s37, s10, 0x187d2000
	s_addc_u32 s42, s11, 0
	s_add_u32 s10, s4, 0x210a000
	s_addc_u32 s11, s5, 0
	s_movk_i32 s43, 0x4040
	s_mov_b32 s99, 0
	s_mov_b32 s13, 0
	s_movk_i32 s58, 0xffe0
	s_movk_i32 s59, 0x600
	v_mov_b64_e32 v[216:217], s[8:9]
	v_mov_b32_e32 v1, 0
	s_movk_i32 s60, 0x300
	s_movk_i32 s61, 0x90
	s_movk_i32 s62, 0x190
	s_mov_b64 s[14:15], 0x18000
	s_mov_b32 s63, 0xff800000
	s_movk_i32 s64, 0x80
	s_movk_i32 s65, 0x7f
	v_mov_b32_e32 v226, 0xff800000
	v_mov_b32_e32 v227, 0x600
	s_branch .LBB0_530

; DI void attn_unit(LAS unsigned char* lds, const bf16_t* __restrict__ Q, const bf16_t* __restrict__ Kg, const bf16_t* __restrict__ VT, bf16_t* __restrict__ MIX, int b, int h, int c0, int nq, int desc) {
;     ...
;       float mx = fmaxf(s0[0], s1[0]);
; #pragma unroll
;       for (int i = 1; i < 16; ++i) mx = fmaxf(mx, fmaxf(s0[i], s1[i]));
;       mx = fmaxf(mx, __shfl_xor(mx, 32));
;       const float mn = fmaxf(mrun, mx);
;       if (__builtin_amdgcn_ballot_w64(mn > mrun) != 0ull) {
;         const float alpha = __builtin_amdgcn_exp2f(mrun - mn); mrun = mn; lrun *= alpha;
; #pragma unroll
;         for (int d = 0; d < 4; ++d) O[d] = O[d] * alpha; }
.LBB0_548:
	s_add_i32 s98, s23, 131072
	s_cmp_eq_u32 s98, s99
	s_cbranch_scc1 .Lpre_LBB0_551
	v_max3_f32 v0, v82, v83, v84
	v_max3_f32 v99, v85, v86, v87
	v_max3_f32 v0, v0, v88, v89
	v_max3_f32 v99, v99, v90, v91
	v_max3_f32 v0, v0, v92, v93
	v_max3_f32 v99, v99, v94, v95
	v_max3_f32 v0, v0, v96, v97
	v_max3_f32 v99, v99, v66, v67
	v_max3_f32 v0, v0, v68, v69
	v_max3_f32 v99, v99, v70, v71
	v_max3_f32 v0, v0, v72, v73
	v_max3_f32 v99, v99, v74, v75
	v_max3_f32 v0, v0, v76, v77
	v_max3_f32 v99, v99, v78, v79
	v_max3_f32 v0, v0, v80, v81
	v_max_f32_e32 v0, v0, v99
	v_mov_b32_e32 v98, v0
	s_nop 1
	v_permlane32_swap_b32_e32 v0, v98
	v_max3_f32 v211, v122, v0, v98
	s_branch .Lpj_LBB0_551
.Lpre_LBB0_551:
	v_max_f32_e32 v211, v122, v241
.Lpj_LBB0_551:
	v_cmp_gt_f32_e32 vcc, v211, v122
	s_cbranch_vccz .LBB0_550
	v_sub_f32_e32 v0, v122, v211
	v_exp_f32_e32 v0, v0
	s_nop 0
	v_pk_mul_f32 v[64:65], v[64:65], v[0:1] op_sel_hi:[1,0]
	v_pk_mul_f32 v[62:63], v[62:63], v[0:1] op_sel_hi:[1,0]
	v_pk_mul_f32 v[60:61], v[60:61], v[0:1] op_sel_hi:[1,0]
	v_pk_mul_f32 v[58:59], v[58:59], v[0:1] op_sel_hi:[1,0]
	v_pk_mul_f32 v[56:57], v[56:57], v[0:1] op_sel_hi:[1,0]
	v_pk_mul_f32 v[54:55], v[54:55], v[0:1] op_sel_hi:[1,0]
	v_pk_mul_f32 v[52:53], v[52:53], v[0:1] op_sel_hi:[1,0]
	v_pk_mul_f32 v[50:51], v[50:51], v[0:1] op_sel_hi:[1,0]
	v_pk_mul_f32 v[48:49], v[48:49], v[0:1] op_sel_hi:[1,0]
	v_pk_mul_f32 v[46:47], v[46:47], v[0:1] op_sel_hi:[1,0]
	v_pk_mul_f32 v[44:45], v[44:45], v[0:1] op_sel_hi:[1,0]
	v_pk_mul_f32 v[42:43], v[42:43], v[0:1] op_sel_hi:[1,0]
	v_pk_mul_f32 v[40:41], v[40:41], v[0:1] op_sel_hi:[1,0]
	v_pk_mul_f32 v[38:39], v[38:39], v[0:1] op_sel_hi:[1,0]
	v_pk_mul_f32 v[36:37], v[36:37], v[0:1] op_sel_hi:[1,0]
	v_pk_mul_f32 v[34:35], v[34:35], v[0:1] op_sel_hi:[1,0]
	v_pk_mul_f32 v[32:33], v[32:33], v[0:1] op_sel_hi:[1,0]
	v_pk_mul_f32 v[30:31], v[30:31], v[0:1] op_sel_hi:[1,0]
	v_pk_mul_f32 v[28:29], v[28:29], v[0:1] op_sel_hi:[1,0]
	v_pk_mul_f32 v[26:27], v[26:27], v[0:1] op_sel_hi:[1,0]
	v_pk_mul_f32 v[24:25], v[24:25], v[0:1] op_sel_hi:[1,0]
	v_pk_mul_f32 v[22:23], v[22:23], v[0:1] op_sel_hi:[1,0]
	v_pk_mul_f32 v[20:21], v[20:21], v[0:1] op_sel_hi:[1,0]
	v_pk_mul_f32 v[18:19], v[18:19], v[0:1] op_sel_hi:[1,0]
	v_pk_mul_f32 v[16:17], v[16:17], v[0:1] op_sel_hi:[1,0]
	v_pk_mul_f32 v[14:15], v[14:15], v[0:1] op_sel_hi:[1,0]
	v_pk_mul_f32 v[12:13], v[12:13], v[0:1] op_sel_hi:[1,0]
	v_pk_mul_f32 v[10:11], v[10:11], v[0:1] op_sel_hi:[1,0]
	v_pk_mul_f32 v[8:9], v[8:9], v[0:1] op_sel_hi:[1,0]
	v_pk_mul_f32 v[6:7], v[6:7], v[0:1] op_sel_hi:[1,0]
	v_pk_mul_f32 v[4:5], v[4:5], v[0:1] op_sel_hi:[1,0]
	v_pk_mul_f32 v[2:3], v[2:3], v[0:1] op_sel_hi:[1,0]
	v_mul_f32_e32 v210, v210, v0
	s_branch .LBB0_551

; #define LAS __attribute__((address_space(3)))
; #define MFMA32(a, b, c) __builtin_amdgcn_mfma_f32_32x32x16_bf16((a), (b), (c), 0, 0, 0)
; DI bf16x8 pack8(const f32x16& x, int s) { u32x4 p; p.x = pk2(x[8 * s], x[8 * s + 1]); p.y = pk2(x[8 * s + 2], x[8 * s + 3]); p.z = pk2(x[8 * s + 4], x[8 * s + 5]); p.w = pk2(x[8 * s + 6], x[8 * s + 7]); return __builtin_bit_cast(bf16x8, p); }
; #define ATT_STOREK(buf) do { _Pragma("unroll") for (int i = 0; i < 3; ++i) *(LAS u32x4*)(lds + (buf) * ATT_KB + klo + 128 * i) = kreg[i]; } while (0)
; #define ATT_STOREV(buf) do { _Pragma("unroll") for (int i = 0; i < 2; ++i) *(LAS u32x4*)(lds + (buf) * ATT_VB + vlo + 64 * i) = vreg[i]; } while (0)
; DI void attn_unit(LAS unsigned char* lds, const bf16_t* __restrict__ Q, const bf16_t* __restrict__ Kg, const bf16_t* __restrict__ VT, bf16_t* __restrict__ MIX, int b, int h, int c0, int nq, int desc) {
;     ...
;       float mx = fmaxf(s0[0], s1[0]);
; #pragma unroll
;       for (int i = 1; i < 16; ++i) mx = fmaxf(mx, fmaxf(s0[i], s1[i]));
;       mx = fmaxf(mx, __shfl_xor(mx, 32));
;     ...
;       float ps = 0.f;
; #pragma unroll
;       for (int i = 0; i < 16; ++i) ps += s0[i] + s1[i];
;       lrun += ps;
;       bf16x8 pf[4]; pf[0] = pack8(s0, 0); pf[1] = pack8(s0, 1); pf[2] = pack8(s1, 0); pf[3] = pack8(s1, 1);
;       const LAS unsigned char* vb = lds + 2 * ATT_KB + buf * ATT_VB + r31 * HROW + 16 * hh;
; #pragma unroll
;       for (int kk = 0; kk < 4; ++kk)
; #pragma unroll
;         for (int d = 0; d < 4; ++d) { const bf16x8 a = *(const LAS bf16x8*)(vb + d * 32 * HROW + 32 * kk); O[d] = MFMA32(a, pf[kk], O[d]); }
;     ...
;     if (t + 2 < nt) ATT_STOREK(buf);
;     if (t + 1 < nt) ATT_STOREV(buf ^ 1);
;     __syncthreads();
;     s0 = n0; s1 = n1;
.Lnok_LBB0_551:
	s_waitcnt lgkmcnt(3)
	v_mfma_f32_32x32x16_bf16 v[2:17], v[234:237], v[82:85], v[2:17]
	ds_read_b128 v[234:237], v223 offset:65056
	v_add_f32_e32 v238, v238, v239
	v_add_f32_e32 v240, v240, v241
	v_mov_b64_e32 v[86:87], v[102:103]
	v_mov_b64_e32 v[94:95], v[110:111]
	s_waitcnt lgkmcnt(3)
	v_mfma_f32_32x32x16_bf16 v[50:65], v[212:215], v[90:93], v[50:65]
	ds_read_b128 v[212:215], v223 offset:51264
	v_add_f32_e32 v0, v238, v240
	v_mov_b64_e32 v[70:71], v[118:119]
	v_mov_b64_e32 v[78:79], v[126:127]
	s_waitcnt lgkmcnt(3)
	v_mfma_f32_32x32x16_bf16 v[34:49], v[218:221], v[90:93], v[34:49]
	ds_read_b128 v[218:221], v223 offset:55872
	v_add_f32_e32 v210, v210, v0
	v_mov_b64_e32 v[88:89], v[104:105]
	v_mov_b64_e32 v[96:97], v[112:113]
	s_waitcnt lgkmcnt(3)
	v_mfma_f32_32x32x16_bf16 v[18:33], v[230:233], v[90:93], v[18:33]
	ds_read_b128 v[230:233], v223 offset:60480
	s_xor_b32 s98, s12, 1
	s_mulk_i32 s98, 0x4800
	v_add_u32_e32 v229, s98, v206
	s_waitcnt vmcnt(0)
	ds_write_b128 v229, v[190:193] offset:51200
	ds_write_b128 v229, v[194:197] offset:51264
	v_max3_f32 v239, v98, v99, v100
	v_max3_f32 v241, v101, v102, v103
	s_waitcnt lgkmcnt(3)
	v_mfma_f32_32x32x16_bf16 v[2:17], v[234:237], v[90:93], v[2:17]
	ds_read_b128 v[234:237], v223 offset:65088
	v_max3_f32 v239, v239, v104, v105
	v_max3_f32 v241, v241, v106, v107
	v_mov_b64_e32 v[72:73], v[120:121]
	v_mov_b64_e32 v[80:81], v[128:129]
	s_waitcnt lgkmcnt(3)
	v_mfma_f32_32x32x16_bf16 v[50:65], v[212:215], v[66:69], v[50:65]
	ds_read_b128 v[212:215], v223 offset:51296
	v_max3_f32 v239, v239, v108, v109
	v_max3_f32 v241, v241, v110, v111
	v_mov_b64_e32 v[82:83], v[98:99]
	v_mov_b64_e32 v[84:85], v[100:101]
	s_waitcnt lgkmcnt(3)
	v_mfma_f32_32x32x16_bf16 v[34:49], v[218:221], v[66:69], v[34:49]
	ds_read_b128 v[218:221], v223 offset:55904
	v_max3_f32 v239, v239, v112, v113
	v_max3_f32 v241, v241, v114, v115
	v_mov_b64_e32 v[90:91], v[106:107]
	v_mov_b64_e32 v[92:93], v[108:109]
	s_waitcnt lgkmcnt(3)
	v_mfma_f32_32x32x16_bf16 v[18:33], v[230:233], v[66:69], v[18:33]
	ds_read_b128 v[230:233], v223 offset:60512
	v_max3_f32 v239, v239, v116, v117
	v_max3_f32 v241, v241, v118, v119
	s_waitcnt lgkmcnt(3)
	v_mfma_f32_32x32x16_bf16 v[2:17], v[234:237], v[66:69], v[2:17]
	ds_read_b128 v[234:237], v223 offset:65120
	v_max3_f32 v239, v239, v120, v121
	v_max3_f32 v241, v241, v122, v123
	s_waitcnt lgkmcnt(3)
	v_mfma_f32_32x32x16_bf16 v[50:65], v[212:215], v[74:77], v[50:65]
	v_max3_f32 v239, v239, v124, v125
	v_max3_f32 v241, v241, v126, v127
	v_mov_b64_e32 v[66:67], v[114:115]
	v_mov_b64_e32 v[68:69], v[116:117]
	s_waitcnt lgkmcnt(2)
	v_mfma_f32_32x32x16_bf16 v[34:49], v[218:221], v[74:77], v[34:49]
	v_max3_f32 v239, v239, v128, v129
	v_max_f32_e32 v241, v239, v241
	s_waitcnt lgkmcnt(1)
	v_mfma_f32_32x32x16_bf16 v[18:33], v[230:233], v[74:77], v[18:33]
	s_waitcnt lgkmcnt(0)
	v_mfma_f32_32x32x16_bf16 v[2:17], v[234:237], v[74:77], v[2:17]
	v_mov_b32_e32 v239, v241
	s_nop 1
	v_permlane32_swap_b32_e32 v241, v239
	v_max_f32_e32 v241, v241, v239
	v_mov_b64_e32 v[74:75], v[122:123]
	v_mov_b64_e32 v[76:77], v[124:125]
	s_add_i32 s99, s23, 131073
	s_or_b64 exec, exec, s[30:31]
	s_branch .LBB0_554
	s_andn2_b64 vcc, exec, s[26:27]
	s_cbranch_vccz .LBB0_560

; DI void attn_unit(LAS unsigned char* lds, const bf16_t* __restrict__ Q, const bf16_t* __restrict__ Kg, const bf16_t* __restrict__ VT, bf16_t* __restrict__ MIX, int b, int h, int c0, int nq, int desc) {
;     ...
;       float mx = fmaxf(s0[0], s1[0]);
; #pragma unroll
;       for (int i = 1; i < 16; ++i) mx = fmaxf(mx, fmaxf(s0[i], s1[i]));
;       mx = fmaxf(mx, __shfl_xor(mx, 32));
;       const float mn = fmaxf(mrun, mx);
;       if (__builtin_amdgcn_ballot_w64(mn > mrun) != 0ull) {
;         const float alpha = __builtin_amdgcn_exp2f(mrun - mn); mrun = mn; lrun *= alpha;
; #pragma unroll
;         for (int d = 0; d < 4; ++d) O[d] = O[d] * alpha; }
.LBB0_580:
	s_add_i32 s98, s70, 65536
	s_cmp_eq_u32 s98, s99
	s_cbranch_scc1 .Lpre_LBB0_583
	v_max3_f32 v0, v112, v113, v114
	v_max3_f32 v3, v115, v116, v117
	v_max3_f32 v0, v0, v118, v119
	v_max3_f32 v3, v3, v120, v121
	v_max3_f32 v0, v0, v122, v123
	v_max3_f32 v3, v3, v124, v125
	v_max3_f32 v0, v0, v126, v127
	v_max3_f32 v3, v3, v96, v97
	v_max3_f32 v0, v0, v98, v99
	v_max3_f32 v3, v3, v100, v101
	v_max3_f32 v0, v0, v102, v103
	v_max3_f32 v3, v3, v104, v105
	v_max3_f32 v0, v0, v106, v107
	v_max3_f32 v3, v3, v108, v109
	v_max3_f32 v0, v0, v110, v111
	v_max_f32_e32 v0, v0, v3
	v_mov_b32_e32 v2, v0
	s_nop 1
	v_permlane32_swap_b32_e32 v0, v2
	v_max3_f32 v234, v94, v0, v2
	s_branch .Lpj_LBB0_583
.Lpre_LBB0_583:
	v_max_f32_e32 v234, v94, v241
.Lpj_LBB0_583:
	v_cmp_gt_f32_e32 vcc, v234, v94
	s_cbranch_vccz .LBB0_582
	v_sub_f32_e32 v0, v94, v234
	v_exp_f32_e32 v0, v0
	s_nop 0
	v_pk_mul_f32 v[78:79], v[78:79], v[0:1] op_sel_hi:[1,0]
	v_pk_mul_f32 v[76:77], v[76:77], v[0:1] op_sel_hi:[1,0]
	v_pk_mul_f32 v[74:75], v[74:75], v[0:1] op_sel_hi:[1,0]
	v_pk_mul_f32 v[72:73], v[72:73], v[0:1] op_sel_hi:[1,0]
	v_pk_mul_f32 v[70:71], v[70:71], v[0:1] op_sel_hi:[1,0]
	v_pk_mul_f32 v[68:69], v[68:69], v[0:1] op_sel_hi:[1,0]
	v_pk_mul_f32 v[66:67], v[66:67], v[0:1] op_sel_hi:[1,0]
	v_pk_mul_f32 v[64:65], v[64:65], v[0:1] op_sel_hi:[1,0]
	v_pk_mul_f32 v[62:63], v[62:63], v[0:1] op_sel_hi:[1,0]
	v_pk_mul_f32 v[60:61], v[60:61], v[0:1] op_sel_hi:[1,0]
	v_pk_mul_f32 v[58:59], v[58:59], v[0:1] op_sel_hi:[1,0]
	v_pk_mul_f32 v[56:57], v[56:57], v[0:1] op_sel_hi:[1,0]
	v_pk_mul_f32 v[54:55], v[54:55], v[0:1] op_sel_hi:[1,0]
	v_pk_mul_f32 v[52:53], v[52:53], v[0:1] op_sel_hi:[1,0]
	v_pk_mul_f32 v[50:51], v[50:51], v[0:1] op_sel_hi:[1,0]
	v_pk_mul_f32 v[48:49], v[48:49], v[0:1] op_sel_hi:[1,0]
	v_pk_mul_f32 v[46:47], v[46:47], v[0:1] op_sel_hi:[1,0]
	v_pk_mul_f32 v[44:45], v[44:45], v[0:1] op_sel_hi:[1,0]
	v_pk_mul_f32 v[42:43], v[42:43], v[0:1] op_sel_hi:[1,0]
	v_pk_mul_f32 v[40:41], v[40:41], v[0:1] op_sel_hi:[1,0]
	v_pk_mul_f32 v[38:39], v[38:39], v[0:1] op_sel_hi:[1,0]
	v_pk_mul_f32 v[36:37], v[36:37], v[0:1] op_sel_hi:[1,0]
	v_pk_mul_f32 v[34:35], v[34:35], v[0:1] op_sel_hi:[1,0]
	v_pk_mul_f32 v[32:33], v[32:33], v[0:1] op_sel_hi:[1,0]
	v_pk_mul_f32 v[30:31], v[30:31], v[0:1] op_sel_hi:[1,0]
	v_pk_mul_f32 v[28:29], v[28:29], v[0:1] op_sel_hi:[1,0]
	v_pk_mul_f32 v[26:27], v[26:27], v[0:1] op_sel_hi:[1,0]
	v_pk_mul_f32 v[24:25], v[24:25], v[0:1] op_sel_hi:[1,0]
	v_pk_mul_f32 v[22:23], v[22:23], v[0:1] op_sel_hi:[1,0]
	v_pk_mul_f32 v[20:21], v[20:21], v[0:1] op_sel_hi:[1,0]
	v_pk_mul_f32 v[18:19], v[18:19], v[0:1] op_sel_hi:[1,0]
	v_pk_mul_f32 v[16:17], v[16:17], v[0:1] op_sel_hi:[1,0]
	v_mul_f32_e32 v80, v80, v0
	s_branch .LBB0_583

; #define LAS __attribute__((address_space(3)))
; #define MFMA32(a, b, c) __builtin_amdgcn_mfma_f32_32x32x16_bf16((a), (b), (c), 0, 0, 0)
; DI bf16x8 pack8(const f32x16& x, int s) { u32x4 p; p.x = pk2(x[8 * s], x[8 * s + 1]); p.y = pk2(x[8 * s + 2], x[8 * s + 3]); p.z = pk2(x[8 * s + 4], x[8 * s + 5]); p.w = pk2(x[8 * s + 6], x[8 * s + 7]); return __builtin_bit_cast(bf16x8, p); }
; #define ATT_STOREK(buf) do { _Pragma("unroll") for (int i = 0; i < 3; ++i) *(LAS u32x4*)(lds + (buf) * ATT_KB + klo + 128 * i) = kreg[i]; } while (0)
; #define ATT_STOREV(buf) do { _Pragma("unroll") for (int i = 0; i < 2; ++i) *(LAS u32x4*)(lds + (buf) * ATT_VB + vlo + 64 * i) = vreg[i]; } while (0)
; DI void attn_unit(LAS unsigned char* lds, const bf16_t* __restrict__ Q, const bf16_t* __restrict__ Kg, const bf16_t* __restrict__ VT, bf16_t* __restrict__ MIX, int b, int h, int c0, int nq, int desc) {
;     ...
;       float mx = fmaxf(s0[0], s1[0]);
; #pragma unroll
;       for (int i = 1; i < 16; ++i) mx = fmaxf(mx, fmaxf(s0[i], s1[i]));
;       mx = fmaxf(mx, __shfl_xor(mx, 32));
;     ...
;       float ps = 0.f;
; #pragma unroll
;       for (int i = 0; i < 16; ++i) ps += s0[i] + s1[i];
;       lrun += ps;
;       bf16x8 pf[4]; pf[0] = pack8(s0, 0); pf[1] = pack8(s0, 1); pf[2] = pack8(s1, 0); pf[3] = pack8(s1, 1);
;       const LAS unsigned char* vb = lds + 2 * ATT_KB + buf * ATT_VB + r31 * HROW + 16 * hh;
; #pragma unroll
;       for (int kk = 0; kk < 4; ++kk)
; #pragma unroll
;         for (int d = 0; d < 4; ++d) { const bf16x8 a = *(const LAS bf16x8*)(vb + d * 32 * HROW + 32 * kk); O[d] = MFMA32(a, pf[kk], O[d]); }
;     ...
;     if (t + 2 < nt) ATT_STOREK(buf);
;     if (t + 1 < nt) ATT_STOREV(buf ^ 1);
;     __syncthreads();
;     s0 = n0; s1 = n1;
.Lnok_LBB0_583:
	s_waitcnt lgkmcnt(3)
	v_mfma_f32_32x32x16_bf16 v[16:31], v[236:239], v[112:115], v[16:31]
	ds_read_b128 v[236:239], v95 offset:65056
	v_add_f32_e32 v14, v14, v15
	v_add_f32_e32 v240, v240, v241
	v_mov_b64_e32 v[116:117], v[132:133]
	v_mov_b64_e32 v[124:125], v[140:141]
	s_waitcnt lgkmcnt(3)
	v_mfma_f32_32x32x16_bf16 v[64:79], v[2:5], v[120:123], v[64:79]
	ds_read_b128 v[2:5], v95 offset:51264
	v_add_f32_e32 v0, v14, v240
	v_mov_b64_e32 v[100:101], v[148:149]
	v_mov_b64_e32 v[108:109], v[156:157]
	s_waitcnt lgkmcnt(3)
	v_mfma_f32_32x32x16_bf16 v[48:63], v[6:9], v[120:123], v[48:63]
	ds_read_b128 v[6:9], v95 offset:55872
	v_add_f32_e32 v80, v80, v0
	v_mov_b64_e32 v[118:119], v[134:135]
	v_mov_b64_e32 v[126:127], v[142:143]
	s_waitcnt lgkmcnt(3)
	v_mfma_f32_32x32x16_bf16 v[32:47], v[10:13], v[120:123], v[32:47]
	ds_read_b128 v[10:13], v95 offset:60480
	s_xor_b32 s98, s71, 1
	s_mulk_i32 s98, 0x4800
	v_add_u32_e32 v235, s98, v230
	s_waitcnt vmcnt(0)
	ds_write_b128 v235, v[160:163] offset:51200
	ds_write_b128 v235, v[164:167] offset:51264
	v_max3_f32 v15, v128, v129, v130
	v_max3_f32 v241, v131, v132, v133
	s_waitcnt lgkmcnt(3)
	v_mfma_f32_32x32x16_bf16 v[16:31], v[236:239], v[120:123], v[16:31]
	ds_read_b128 v[236:239], v95 offset:65088
	v_max3_f32 v15, v15, v134, v135
	v_max3_f32 v241, v241, v136, v137
	v_mov_b64_e32 v[102:103], v[150:151]
	v_mov_b64_e32 v[110:111], v[158:159]
	s_waitcnt lgkmcnt(3)
	v_mfma_f32_32x32x16_bf16 v[64:79], v[2:5], v[96:99], v[64:79]
	ds_read_b128 v[2:5], v95 offset:51296
	v_max3_f32 v15, v15, v138, v139
	v_max3_f32 v241, v241, v140, v141
	v_mov_b64_e32 v[112:113], v[128:129]
	v_mov_b64_e32 v[114:115], v[130:131]
	s_waitcnt lgkmcnt(3)
	v_mfma_f32_32x32x16_bf16 v[48:63], v[6:9], v[96:99], v[48:63]
	ds_read_b128 v[6:9], v95 offset:55904
	v_max3_f32 v15, v15, v142, v143
	v_max3_f32 v241, v241, v144, v145
	v_mov_b64_e32 v[120:121], v[136:137]
	v_mov_b64_e32 v[122:123], v[138:139]
	s_waitcnt lgkmcnt(3)
	v_mfma_f32_32x32x16_bf16 v[32:47], v[10:13], v[96:99], v[32:47]
	ds_read_b128 v[10:13], v95 offset:60512
	v_max3_f32 v15, v15, v146, v147
	v_max3_f32 v241, v241, v148, v149
	s_waitcnt lgkmcnt(3)
	v_mfma_f32_32x32x16_bf16 v[16:31], v[236:239], v[96:99], v[16:31]
	ds_read_b128 v[236:239], v95 offset:65120
	v_max3_f32 v15, v15, v150, v151
	v_max3_f32 v241, v241, v152, v153
	s_waitcnt lgkmcnt(3)
	v_mfma_f32_32x32x16_bf16 v[64:79], v[2:5], v[104:107], v[64:79]
	v_max3_f32 v15, v15, v154, v155
	v_max3_f32 v241, v241, v156, v157
	v_mov_b64_e32 v[96:97], v[144:145]
	v_mov_b64_e32 v[98:99], v[146:147]
	s_waitcnt lgkmcnt(2)
	v_mfma_f32_32x32x16_bf16 v[48:63], v[6:9], v[104:107], v[48:63]
	v_max3_f32 v15, v15, v158, v159
	v_max_f32_e32 v241, v15, v241
	s_waitcnt lgkmcnt(1)
	v_mfma_f32_32x32x16_bf16 v[32:47], v[10:13], v[104:107], v[32:47]
	s_waitcnt lgkmcnt(0)
	v_mfma_f32_32x32x16_bf16 v[16:31], v[236:239], v[104:107], v[16:31]
	v_mov_b32_e32 v15, v241
	s_nop 1
	v_permlane32_swap_b32_e32 v241, v15
	v_max_f32_e32 v241, v241, v15
	v_mov_b64_e32 v[104:105], v[152:153]
	v_mov_b64_e32 v[106:107], v[154:155]
	s_add_i32 s99, s70, 65537
	s_add_i32 s99, s70, 65537
	s_or_b64 exec, exec, s[6:7]
	s_branch .LBB0_586
	s_andn2_b64 vcc, exec, s[26:27]
	s_cbranch_vccz .LBB0_592

; #define ATT_LOADK(t) do { const bf16_t* kp_ = kbase + (size_t)(64 * (t)) * 768 + kgo; _Pragma("unroll") for (int i = 0; i < 3; ++i) kreg[i] = *(const u32x4*)(kp_ + 64 * i); } while (0)
; #define ATT_LOADV(t) do { const bf16_t* vp_ = vbase + 64 * (t) + vgo; _Pragma("unroll") for (int i = 0; i < 2; ++i) vreg[i] = *(const u32x4*)(vp_ + 32 * i); } while (0)
; #define ATT_STOREK(buf) do { _Pragma("unroll") for (int i = 0; i < 3; ++i) *(LAS u32x4*)(lds + (buf) * ATT_KB + klo + 128 * i) = kreg[i]; } while (0)
; #define ATT_STOREV(buf) do { _Pragma("unroll") for (int i = 0; i < 2; ++i) *(LAS u32x4*)(lds + (buf) * ATT_VB + vlo + 64 * i) = vreg[i]; } while (0)
; DI void attn_unit(LAS unsigned char* lds, const bf16_t* __restrict__ Q, const bf16_t* __restrict__ Kg, const bf16_t* __restrict__ VT, bf16_t* __restrict__ MIX, int b, int h, int c0, int nq, int desc) {
;     ...
;   for (int t = 0; t < nt; ++t) {
;     const int buf = t & 1; const int tau = TAU(t), taun = TAU(t + 1);
;     if (t + 2 < nt) ATT_LOADK(TAU(t + 2));
;     if (t + 1 < nt) ATT_LOADV(taun);
;     const bool do_cur = active && tau <= cq; const bool do_next = active && (taun <= cq) && (t + 1 < nt);
;     ...
;     if (t + 2 < nt) ATT_STOREK(buf);
;     if (t + 1 < nt) ATT_STOREV(buf ^ 1);
;     __syncthreads();
;     s0 = n0; s1 = n1;
.LBB0_586:
	s_add_i32 s70, s70, 1
	s_add_i32 s6, s68, s70
	s_sub_i32 s69, s69, 64
	s_add_i32 s16, s16, -1
	s_cmp_eq_u32 s6, 2
	s_waitcnt lgkmcnt(0)
	s_barrier
	s_cbranch_scc1 .LBB0_594
	s_add_i32 s98, s70, 65536
	s_cmp_eq_u32 s98, s99
	s_cbranch_scc1 .Lskipcp_LBB0_583
	v_mov_b64_e32 v[112:113], v[128:129]
	v_mov_b64_e32 v[96:97], v[144:145]
	v_mov_b64_e32 v[114:115], v[130:131]
	v_mov_b64_e32 v[116:117], v[132:133]
	v_mov_b64_e32 v[118:119], v[134:135]
	v_mov_b64_e32 v[120:121], v[136:137]
	v_mov_b64_e32 v[122:123], v[138:139]
	v_mov_b64_e32 v[124:125], v[140:141]
	v_mov_b64_e32 v[126:127], v[142:143]
	v_mov_b64_e32 v[98:99], v[146:147]
	v_mov_b64_e32 v[100:101], v[148:149]
	v_mov_b64_e32 v[102:103], v[150:151]
	v_mov_b64_e32 v[104:105], v[152:153]
	v_mov_b64_e32 v[106:107], v[154:155]
	v_mov_b64_e32 v[108:109], v[156:157]
	v_mov_b64_e32 v[110:111], v[158:159]
.Lskipcp_LBB0_583:
	v_mov_b32_e32 v94, v234
	s_cmp_lt_i32 s70, s17
	s_cselect_b64 s[26:27], -1, 0
	s_cmp_ge_i32 s70, s17
	s_cbranch_scc0 .LBB0_570
	s_branch .LBB0_571

; #define LAS __attribute__((address_space(3)))
; DI int obid() { int t = blockIdx.x; asm volatile("" : "+s"(t)); return t; }
; DI int ogrid() { int t = gridDim.x; asm volatile("" : "+s"(t)); return t; }
; DI int otid() { int t = threadIdx.x; asm volatile("" : "+v"(t)); return t; }
; DI unsigned char* opq(unsigned char* p) { asm volatile("" : "+s"(p)); return p; }
; #define P (kparams())
; DI void attn_unit(LAS unsigned char* lds, const bf16_t* __restrict__ Q, const bf16_t* __restrict__ Kg, const bf16_t* __restrict__ VT, bf16_t* __restrict__ MIX, int b, int h, int c0, int nq, int desc) {
;   const int tid = otid(), wave = tid >> 6, lane = tid & 63, r31 = lane & 31, hh = lane >> 5;
;   const bool active = (wave >> 1) < nq; const int cq = c0 + (wave >> 1); const int nt = c0 + nq;
;   const size_t qrow = (size_t)b * LP + 64 * c0 + (active ? 32 * wave + r31 : 0);
;   bf16x8 qf[12];
;   { const bf16_t* qp = Q + qrow * 768 + h * 192 + 8 * hh;
; #pragma unroll
;     for (int s = 0; s < 12; ++s) qf[s] = *(const bf16x8*)(qp + 16 * s); }
;   f32x16 O[4];
; #pragma unroll
;   for (int d = 0; d < 4; ++d)
; #pragma unroll
;     for (int i = 0; i < 16; ++i) O[d][i] = 0.f;
;   float mrun = NEG_INF, lrun = 0.f;
;   const bf16_t* kbase = Kg + (size_t)b * LP * 768 + h * 192;
;   const bf16_t* vbase = VT + (size_t)(b * 4 + h) * 128 * LP;
; DI void phase_attn(KP P, LAS unsigned char* lds) {
;   const bf16_t* Q = (const bf16_t*)(opq(P->ws) + OFF_BIG + B_QP); const bf16_t* Kg = (const bf16_t*)(opq(P->ws) + OFF_BIG + B_KK); const bf16_t* VT = (const bf16_t*)(opq(P->ws) + OFF_BIG + B_VT);
;   bf16_t* MIX = (bf16_t*)(opq(P->ws) + OFF_U);
;   for (int j = obid(); j < 256; j += ogrid()) {
;     const int bh = j & 7, pi = j >> 3; const int b = bh >> 2, h = bh & 3;
;     attn_unit(lds, Q, Kg, VT, MIX, b, h, 4 * (64 - pi) - 3, 4, 0);
.LBB0_2537:
	s_or_b64 exec, exec, s[58:59]
	s_mov_b64 s[4:5], s[88:89]
	s_waitcnt lgkmcnt(0)
	s_barrier
	s_load_dwordx2 s[4:5], s[4:5], 0x98
	v_readlane_b32 s3, v254, 12
	s_waitcnt lgkmcnt(0)
	s_mov_b64 s[8:9], s[4:5]
	s_mov_b64 s[6:7], s[4:5]
	s_mov_b64 s[10:11], s[4:5]
	s_cmpk_gt_i32 s3, 0xff
	s_cbranch_scc1 .LBB0_2638
	s_add_u32 s8, s8, 0x12712000
	s_addc_u32 s9, s9, 0
	s_add_u32 s33, s6, 0x15772000
	s_addc_u32 s36, s7, 0
	s_add_u32 s37, s10, 0x187d2000
	s_addc_u32 s42, s11, 0
	s_add_u32 s10, s4, 0x210a000
	s_addc_u32 s11, s5, 0
	s_movk_i32 s43, 0x4040
	s_mov_b32 s99, 0
	s_mov_b32 s13, 0
	s_movk_i32 s58, 0xffe0
	s_movk_i32 s59, 0x600
	v_mov_b64_e32 v[216:217], s[8:9]
	v_mov_b32_e32 v1, 0
	s_movk_i32 s60, 0x300
	s_movk_i32 s61, 0x90
	s_movk_i32 s62, 0x190
	s_mov_b64 s[14:15], 0x18000
	s_mov_b32 s63, 0xff800000
	s_movk_i32 s64, 0x80
	s_movk_i32 s65, 0x7f
	v_mov_b32_e32 v226, 0xff800000
	v_mov_b32_e32 v227, 0x600
	s_branch .LBB0_2541

; DI void attn_unit(LAS unsigned char* lds, const bf16_t* __restrict__ Q, const bf16_t* __restrict__ Kg, const bf16_t* __restrict__ VT, bf16_t* __restrict__ MIX, int b, int h, int c0, int nq, int desc) {
;     ...
;       float mx = fmaxf(s0[0], s1[0]);
; #pragma unroll
;       for (int i = 1; i < 16; ++i) mx = fmaxf(mx, fmaxf(s0[i], s1[i]));
;       mx = fmaxf(mx, __shfl_xor(mx, 32));
;       const float mn = fmaxf(mrun, mx);
;       if (__builtin_amdgcn_ballot_w64(mn > mrun) != 0ull) {
;         const float alpha = __builtin_amdgcn_exp2f(mrun - mn); mrun = mn; lrun *= alpha;
; #pragma unroll
;         for (int d = 0; d < 4; ++d) O[d] = O[d] * alpha; }
.LBB0_2591:
	s_add_i32 s98, s70, 65536
	s_cmp_eq_u32 s98, s99
	s_cbranch_scc1 .Lpre_LBB0_2594
	v_max3_f32 v0, v112, v113, v114
	v_max3_f32 v3, v115, v116, v117
	v_max3_f32 v0, v0, v118, v119
	v_max3_f32 v3, v3, v120, v121
	v_max3_f32 v0, v0, v122, v123
	v_max3_f32 v3, v3, v124, v125
	v_max3_f32 v0, v0, v126, v127
	v_max3_f32 v3, v3, v96, v97
	v_max3_f32 v0, v0, v98, v99
	v_max3_f32 v3, v3, v100, v101
	v_max3_f32 v0, v0, v102, v103
	v_max3_f32 v3, v3, v104, v105
	v_max3_f32 v0, v0, v106, v107
	v_max3_f32 v3, v3, v108, v109
	v_max3_f32 v0, v0, v110, v111
	v_max_f32_e32 v0, v0, v3
	v_mov_b32_e32 v2, v0
	s_nop 1
	v_permlane32_swap_b32_e32 v0, v2
	v_max3_f32 v233, v94, v0, v2
	s_branch .Lpj_LBB0_2594
.Lpre_LBB0_2594:
	v_max_f32_e32 v233, v94, v241
.Lpj_LBB0_2594:
	v_cmp_gt_f32_e32 vcc, v233, v94
	s_cbranch_vccz .LBB0_2593
	v_sub_f32_e32 v0, v94, v233
	v_exp_f32_e32 v0, v0
	s_nop 0
	v_pk_mul_f32 v[78:79], v[78:79], v[0:1] op_sel_hi:[1,0]
	v_pk_mul_f32 v[76:77], v[76:77], v[0:1] op_sel_hi:[1,0]
	v_pk_mul_f32 v[74:75], v[74:75], v[0:1] op_sel_hi:[1,0]
	v_pk_mul_f32 v[72:73], v[72:73], v[0:1] op_sel_hi:[1,0]
	v_pk_mul_f32 v[70:71], v[70:71], v[0:1] op_sel_hi:[1,0]
	v_pk_mul_f32 v[68:69], v[68:69], v[0:1] op_sel_hi:[1,0]
	v_pk_mul_f32 v[66:67], v[66:67], v[0:1] op_sel_hi:[1,0]
	v_pk_mul_f32 v[64:65], v[64:65], v[0:1] op_sel_hi:[1,0]
	v_pk_mul_f32 v[62:63], v[62:63], v[0:1] op_sel_hi:[1,0]
	v_pk_mul_f32 v[60:61], v[60:61], v[0:1] op_sel_hi:[1,0]
	v_pk_mul_f32 v[58:59], v[58:59], v[0:1] op_sel_hi:[1,0]
	v_pk_mul_f32 v[56:57], v[56:57], v[0:1] op_sel_hi:[1,0]
	v_pk_mul_f32 v[54:55], v[54:55], v[0:1] op_sel_hi:[1,0]
	v_pk_mul_f32 v[52:53], v[52:53], v[0:1] op_sel_hi:[1,0]
	v_pk_mul_f32 v[50:51], v[50:51], v[0:1] op_sel_hi:[1,0]
	v_pk_mul_f32 v[48:49], v[48:49], v[0:1] op_sel_hi:[1,0]
	v_pk_mul_f32 v[46:47], v[46:47], v[0:1] op_sel_hi:[1,0]
	v_pk_mul_f32 v[44:45], v[44:45], v[0:1] op_sel_hi:[1,0]
	v_pk_mul_f32 v[42:43], v[42:43], v[0:1] op_sel_hi:[1,0]
	v_pk_mul_f32 v[40:41], v[40:41], v[0:1] op_sel_hi:[1,0]
	v_pk_mul_f32 v[38:39], v[38:39], v[0:1] op_sel_hi:[1,0]
	v_pk_mul_f32 v[36:37], v[36:37], v[0:1] op_sel_hi:[1,0]
	v_pk_mul_f32 v[34:35], v[34:35], v[0:1] op_sel_hi:[1,0]
	v_pk_mul_f32 v[32:33], v[32:33], v[0:1] op_sel_hi:[1,0]
	v_pk_mul_f32 v[30:31], v[30:31], v[0:1] op_sel_hi:[1,0]
	v_pk_mul_f32 v[28:29], v[28:29], v[0:1] op_sel_hi:[1,0]
	v_pk_mul_f32 v[26:27], v[26:27], v[0:1] op_sel_hi:[1,0]
	v_pk_mul_f32 v[24:25], v[24:25], v[0:1] op_sel_hi:[1,0]
	v_pk_mul_f32 v[22:23], v[22:23], v[0:1] op_sel_hi:[1,0]
	v_pk_mul_f32 v[20:21], v[20:21], v[0:1] op_sel_hi:[1,0]
	v_pk_mul_f32 v[18:19], v[18:19], v[0:1] op_sel_hi:[1,0]
	v_pk_mul_f32 v[16:17], v[16:17], v[0:1] op_sel_hi:[1,0]
	v_mul_f32_e32 v80, v80, v0
	s_branch .LBB0_2594

; #define LAS __attribute__((address_space(3)))
; #define MFMA32(a, b, c) __builtin_amdgcn_mfma_f32_32x32x16_bf16((a), (b), (c), 0, 0, 0)
; DI void attn_unit(LAS unsigned char* lds, const bf16_t* __restrict__ Q, const bf16_t* __restrict__ Kg, const bf16_t* __restrict__ VT, bf16_t* __restrict__ MIX, int b, int h, int c0, int nq, int desc) {
;     ...
;       float mx = fmaxf(s0[0], s1[0]);
; #pragma unroll
;       for (int i = 1; i < 16; ++i) mx = fmaxf(mx, fmaxf(s0[i], s1[i]));
;       mx = fmaxf(mx, __shfl_xor(mx, 32));
;     ...
;       const LAS unsigned char* vb = lds + 2 * ATT_KB + buf * ATT_VB + r31 * HROW + 16 * hh;
; #pragma unroll
;       for (int kk = 0; kk < 4; ++kk)
; #pragma unroll
;         for (int d = 0; d < 4; ++d) { const bf16x8 a = *(const LAS bf16x8*)(vb + d * 32 * HROW + 32 * kk); O[d] = MFMA32(a, pf[kk], O[d]); }
.Lnok_LBB0_2594:
	s_waitcnt lgkmcnt(3)
	v_mfma_f32_32x32x16_bf16 v[16:31], v[236:239], v[112:115], v[16:31]
	ds_read_b128 v[236:239], v95 offset:65056
	v_add_f32_e32 v14, v14, v15
	v_add_f32_e32 v240, v240, v241
	v_mov_b64_e32 v[116:117], v[132:133]
	v_mov_b64_e32 v[124:125], v[140:141]
	s_waitcnt lgkmcnt(3)
	v_mfma_f32_32x32x16_bf16 v[64:79], v[2:5], v[120:123], v[64:79]
	ds_read_b128 v[2:5], v95 offset:51264
	v_add_f32_e32 v0, v14, v240
	v_mov_b64_e32 v[100:101], v[148:149]
	v_mov_b64_e32 v[108:109], v[156:157]
	s_waitcnt lgkmcnt(3)
	v_mfma_f32_32x32x16_bf16 v[48:63], v[6:9], v[120:123], v[48:63]
	ds_read_b128 v[6:9], v95 offset:55872
	v_add_f32_e32 v80, v80, v0
	v_mov_b64_e32 v[118:119], v[134:135]
	v_mov_b64_e32 v[126:127], v[142:143]
	s_waitcnt lgkmcnt(3)
	v_mfma_f32_32x32x16_bf16 v[32:47], v[10:13], v[120:123], v[32:47]
	ds_read_b128 v[10:13], v95 offset:60480
	s_xor_b32 s98, s71, 1
	s_mulk_i32 s98, 0x4800
	v_add_u32_e32 v235, s98, v229
	s_waitcnt vmcnt(0)
	ds_write_b128 v235, v[160:163] offset:51200
	ds_write_b128 v235, v[164:167] offset:51264
	v_max3_f32 v15, v128, v129, v130
	v_max3_f32 v241, v131, v132, v133
	s_waitcnt lgkmcnt(3)
	v_mfma_f32_32x32x16_bf16 v[16:31], v[236:239], v[120:123], v[16:31]
	ds_read_b128 v[236:239], v95 offset:65088
	v_max3_f32 v15, v15, v134, v135
	v_max3_f32 v241, v241, v136, v137
	v_mov_b64_e32 v[102:103], v[150:151]
	v_mov_b64_e32 v[110:111], v[158:159]
	s_waitcnt lgkmcnt(3)
	v_mfma_f32_32x32x16_bf16 v[64:79], v[2:5], v[96:99], v[64:79]
	ds_read_b128 v[2:5], v95 offset:51296
	v_max3_f32 v15, v15, v138, v139
	v_max3_f32 v241, v241, v140, v141
	v_mov_b64_e32 v[112:113], v[128:129]
	v_mov_b64_e32 v[114:115], v[130:131]
	s_waitcnt lgkmcnt(3)
	v_mfma_f32_32x32x16_bf16 v[48:63], v[6:9], v[96:99], v[48:63]
	ds_read_b128 v[6:9], v95 offset:55904
	v_max3_f32 v15, v15, v142, v143
	v_max3_f32 v241, v241, v144, v145
	v_mov_b64_e32 v[120:121], v[136:137]
	v_mov_b64_e32 v[122:123], v[138:139]
	s_waitcnt lgkmcnt(3)
	v_mfma_f32_32x32x16_bf16 v[32:47], v[10:13], v[96:99], v[32:47]
	ds_read_b128 v[10:13], v95 offset:60512
	v_max3_f32 v15, v15, v146, v147
	v_max3_f32 v241, v241, v148, v149
	s_waitcnt lgkmcnt(3)
	v_mfma_f32_32x32x16_bf16 v[16:31], v[236:239], v[96:99], v[16:31]
	ds_read_b128 v[236:239], v95 offset:65120
	v_max3_f32 v15, v15, v150, v151
	v_max3_f32 v241, v241, v152, v153
	s_waitcnt lgkmcnt(3)
	v_mfma_f32_32x32x16_bf16 v[64:79], v[2:5], v[104:107], v[64:79]
	v_max3_f32 v15, v15, v154, v155
	v_max3_f32 v241, v241, v156, v157
	v_mov_b64_e32 v[96:97], v[144:145]
	v_mov_b64_e32 v[98:99], v[146:147]
	s_waitcnt lgkmcnt(2)
	v_mfma_f32_32x32x16_bf16 v[48:63], v[6:9], v[104:107], v[48:63]
	v_max3_f32 v15, v15, v158, v159
	v_max_f32_e32 v241, v15, v241
	s_waitcnt lgkmcnt(1)
	v_mfma_f32_32x32x16_bf16 v[32:47], v[10:13], v[104:107], v[32:47]
	s_waitcnt lgkmcnt(0)
	v_mfma_f32_32x32x16_bf16 v[16:31], v[236:239], v[104:107], v[16:31]
	v_mov_b32_e32 v15, v241
	s_nop 1
	v_permlane32_swap_b32_e32 v241, v15
	v_max_f32_e32 v241, v241, v15
	v_mov_b64_e32 v[104:105], v[152:153]
	v_mov_b64_e32 v[106:107], v[154:155]
	s_add_i32 s99, s70, 65537
	s_add_i32 s99, s70, 65537
	s_or_b64 exec, exec, s[6:7]
	s_branch .LBB0_2597
	s_andn2_b64 vcc, exec, s[26:27]
	s_cbranch_vccz .LBB0_2603

; #define ATT_STOREK(buf) do { _Pragma("unroll") for (int i = 0; i < 3; ++i) *(LAS u32x4*)(lds + (buf) * ATT_KB + klo + 128 * i) = kreg[i]; } while (0)
; #define ATT_STOREV(buf) do { _Pragma("unroll") for (int i = 0; i < 2; ++i) *(LAS u32x4*)(lds + (buf) * ATT_VB + vlo + 64 * i) = vreg[i]; } while (0)
; DI void attn_unit(LAS unsigned char* lds, const bf16_t* __restrict__ Q, const bf16_t* __restrict__ Kg, const bf16_t* __restrict__ VT, bf16_t* __restrict__ MIX, int b, int h, int c0, int nq, int desc) {
;     ...
;     if (t + 2 < nt) ATT_STOREK(buf);
;     if (t + 1 < nt) ATT_STOREV(buf ^ 1);
;     __syncthreads();
;     s0 = n0; s1 = n1;
.LBB0_2597:
	s_add_i32 s70, s70, 1
	s_add_i32 s0, s68, s70
	s_sub_i32 s69, s69, 64
	s_add_i32 s16, s16, -1
	s_cmp_eq_u32 s0, 2
	s_waitcnt lgkmcnt(0)
	s_barrier
	s_cbranch_scc1 .LBB0_2605
	s_add_i32 s98, s70, 65536
	s_cmp_eq_u32 s98, s99
	s_cbranch_scc1 .Lskipcp_LBB0_2594
	v_mov_b64_e32 v[112:113], v[128:129]
	v_mov_b64_e32 v[96:97], v[144:145]
	v_mov_b64_e32 v[114:115], v[130:131]
	v_mov_b64_e32 v[116:117], v[132:133]
	v_mov_b64_e32 v[118:119], v[134:135]
	v_mov_b64_e32 v[120:121], v[136:137]
	v_mov_b64_e32 v[122:123], v[138:139]
	v_mov_b64_e32 v[124:125], v[140:141]
	v_mov_b64_e32 v[126:127], v[142:143]
	v_mov_b64_e32 v[98:99], v[146:147]
	v_mov_b64_e32 v[100:101], v[148:149]
	v_mov_b64_e32 v[102:103], v[150:151]
	v_mov_b64_e32 v[104:105], v[152:153]
	v_mov_b64_e32 v[106:107], v[154:155]
	v_mov_b64_e32 v[108:109], v[156:157]
	v_mov_b64_e32 v[110:111], v[158:159]
.Lskipcp_LBB0_2594:
	v_mov_b32_e32 v94, v233
	s_cmp_lt_i32 s70, s17
	s_cselect_b64 s[26:27], -1, 0
	s_cmp_ge_i32 s70, s17
	s_cbranch_scc0 .LBB0_2581
	s_branch .LBB0_2582
